# RoPE GEMM instance tile head: next-tile index math specialised for the group size 8 of this problem (shift + mask instead of the general float-reciprocal division)
# baseline (speedup 1.0000x reference)
; template <class Epi>
; __device__ __forceinline__ void gemm_phase(const bf16_t* __restrict__ A, const bf16_t* __restrict__ Bt, int M, int N, LAS unsigned char* lds, const Epi& epi, int vcu) {
;     ...
;     auto tile_rc = [&](int it, int& brow, int& bcol) -> bool {
;         const long Lq = (long)it * gridDim.x + vcu; if (Lq >= nwg) return false;
;         int wgid = (int)Lq; { const int q = nwg / NXCD, r = nwg % NXCD, xcd = wgid % NXCD, off = wgid / NXCD; wgid = (xcd < r ? xcd * (q + 1) : r * (q + 1) + (xcd - r) * q) + off; }
;         const int nig = WGM * nN, gid = wgid / nig, fm = gid * WGM, gsz = (nM - fm) < WGM ? (nM - fm) : WGM;
;         brow = (fm + ((wgid % nig) % gsz)) * BM; bcol = ((wgid % nig) / gsz) * BM; return true;
.LBB0_252:
	s_add_i32 s29, s29, 1
	s_mul_i32 s10, s29, s50
	s_mul_hi_u32 s5, s29, s50
	s_add_u32 s52, s10, s20
	s_addc_u32 s53, s5, s22
	v_mov_b64_e32 v[2:3], s[48:49]
	v_cmp_ge_i64_e64 s[40:41], s[52:53], v[2:3]
	s_mov_b32 s93, s73
	s_mov_b64 s[72:73], s[12:13]
	s_mov_b32 s92, s87
	s_mov_b32 s87, s86
	s_mov_b32 s86, s36
	s_mov_b32 s13, s70
	s_mov_b32 s12, s83
	s_and_b64 vcc, exec, s[40:41]
	s_mov_b32 s5, s42
	s_mov_b32 s78, s44
	s_cbranch_vccnz .LBB0_254
	s_ashr_i32 s5, s52, 31
	s_lshr_b32 s5, s5, 29
	s_add_i32 s5, s52, s5
	s_ashr_i32 s10, s5, 3
	s_and_b32 s5, s5, -8
	s_sub_i32 s5, s52, s5
	s_lshr_b32 s11, s5, 31
	s_or_b32 s11, s23, s11
	s_mul_i32 s5, s11, s5
	s_add_i32 s5, s5, s10
	s_abs_i32 s11, s5
	s_mul_hi_u32 s43, s11, s71
	s_mul_i32 s45, s43, s64
	s_sub_i32 s11, s11, s45
	s_ashr_i32 s10, s5, 31
	s_add_i32 s45, s43, 1
	s_sub_i32 s52, s11, s64
	s_cmp_ge_u32 s11, s64
	s_cselect_b32 s43, s45, s43
	s_cselect_b32 s11, s52, s11
	s_add_i32 s45, s43, 1
	s_cmp_ge_u32 s11, s64
	s_cselect_b32 s11, s45, s43
	s_xor_b32 s11, s11, s10
	s_sub_i32 s10, s11, s10
	s_lshl_b32 s11, s10, 3
	s_mul_i32 s10, s10, s64
	s_sub_i32 s5, s5, s10
	s_lshr_b32 s10, s5, 3
	s_and_b32 s5, s5, 7
	s_add_i32 s5, s5, s11
	s_lshl_b32 s5, s5, 8
	s_lshl_b32 s78, s10, 8
